# P0 weight-transpose load loops fully unrolled (32 loads in flight per wave) on top of the pipelined diff-attention loop
# baseline (speedup 1.0000x reference)
; #define LAS __attribute__((address_space(3)))
; #define LDS_WAIT() asm volatile("s_waitcnt lgkmcnt(0)" ::: "memory")
; template <bool NT_STORE> __device__ __forceinline__ void p0_transpose_item(const float* W, int ldw, int src_col0, bf16* WT, int K, int dst_row0, int k0, LAS float* scr, int lane, const float* kscale = nullptr) {
; #pragma unroll 8
;     for (int i = 0; i < 32; ++i) { const int kk = 2 * i + (lane >> 5); scr[kk * 33 + (lane & 31)] = __builtin_nontemporal_load(W + (size_t)(k0 + kk) * ldw + src_col0 + (lane & 31)); }
;     LDS_WAIT(); asm volatile("" ::: "memory");
.LBB0_36:
	v_add_u32_e32 v28, s18, v2
	v_add_u32_e32 v8, 0xfe000000, v28
	v_lshl_add_u64 v[4:5], v[8:9], 2, v[0:1]
	v_add_u32_e32 v8, 0xfe001000, v28
	v_lshl_add_u64 v[6:7], v[8:9], 2, v[0:1]
	v_add_u32_e32 v8, 0xfe002000, v28
	global_load_dword v188, v[4:5], off nt
	global_load_dword v189, v[6:7], off nt
	v_lshl_add_u64 v[4:5], v[8:9], 2, v[0:1]
	v_add_u32_e32 v8, 0xfe003000, v28
	v_lshl_add_u64 v[6:7], v[8:9], 2, v[0:1]
	v_add_u32_e32 v8, 0xfe004000, v28
	global_load_dword v190, v[4:5], off nt
	global_load_dword v191, v[6:7], off nt
	v_lshl_add_u64 v[4:5], v[8:9], 2, v[0:1]
	v_add_u32_e32 v8, 0xfe005000, v28
	v_lshl_add_u64 v[6:7], v[8:9], 2, v[0:1]
	v_add_u32_e32 v8, 0xfe006000, v28
	global_load_dword v192, v[4:5], off nt
	global_load_dword v193, v[6:7], off nt
	v_lshl_add_u64 v[4:5], v[8:9], 2, v[0:1]
	v_add_u32_e32 v8, 0xfe007000, v28
	v_lshl_add_u64 v[6:7], v[8:9], 2, v[0:1]
	global_load_dword v194, v[4:5], off nt
	global_load_dword v195, v[6:7], off nt
	s_add_i32 s18, s18, 0x8000
	v_add_u32_e32 v28, s18, v2
	v_add_u32_e32 v8, 0xfe000000, v28
	v_lshl_add_u64 v[4:5], v[8:9], 2, v[0:1]
	v_add_u32_e32 v8, 0xfe001000, v28
	v_lshl_add_u64 v[6:7], v[8:9], 2, v[0:1]
	v_add_u32_e32 v8, 0xfe002000, v28
	global_load_dword v196, v[4:5], off nt
	global_load_dword v197, v[6:7], off nt
	v_lshl_add_u64 v[4:5], v[8:9], 2, v[0:1]
	v_add_u32_e32 v8, 0xfe003000, v28
	v_lshl_add_u64 v[6:7], v[8:9], 2, v[0:1]
	v_add_u32_e32 v8, 0xfe004000, v28
	global_load_dword v198, v[4:5], off nt
	global_load_dword v199, v[6:7], off nt
	v_lshl_add_u64 v[4:5], v[8:9], 2, v[0:1]
	v_add_u32_e32 v8, 0xfe005000, v28
	v_lshl_add_u64 v[6:7], v[8:9], 2, v[0:1]
	v_add_u32_e32 v8, 0xfe006000, v28
	global_load_dword v200, v[4:5], off nt
	global_load_dword v201, v[6:7], off nt
	v_lshl_add_u64 v[4:5], v[8:9], 2, v[0:1]
	v_add_u32_e32 v8, 0xfe007000, v28
	v_lshl_add_u64 v[6:7], v[8:9], 2, v[0:1]
	global_load_dword v202, v[4:5], off nt
	global_load_dword v203, v[6:7], off nt
	s_add_i32 s18, s18, 0x8000
	v_add_u32_e32 v28, s18, v2
	v_add_u32_e32 v8, 0xfe000000, v28
	v_lshl_add_u64 v[4:5], v[8:9], 2, v[0:1]
	v_add_u32_e32 v8, 0xfe001000, v28
	v_lshl_add_u64 v[6:7], v[8:9], 2, v[0:1]
	v_add_u32_e32 v8, 0xfe002000, v28
	global_load_dword v204, v[4:5], off nt
	global_load_dword v205, v[6:7], off nt
	v_lshl_add_u64 v[4:5], v[8:9], 2, v[0:1]
	v_add_u32_e32 v8, 0xfe003000, v28
	v_lshl_add_u64 v[6:7], v[8:9], 2, v[0:1]
	v_add_u32_e32 v8, 0xfe004000, v28
	global_load_dword v206, v[4:5], off nt
	global_load_dword v207, v[6:7], off nt
	v_lshl_add_u64 v[4:5], v[8:9], 2, v[0:1]
	v_add_u32_e32 v8, 0xfe005000, v28
	v_lshl_add_u64 v[6:7], v[8:9], 2, v[0:1]
	v_add_u32_e32 v8, 0xfe006000, v28
	global_load_dword v208, v[4:5], off nt
	global_load_dword v209, v[6:7], off nt
	v_lshl_add_u64 v[4:5], v[8:9], 2, v[0:1]
	v_add_u32_e32 v8, 0xfe007000, v28
	v_lshl_add_u64 v[6:7], v[8:9], 2, v[0:1]
	global_load_dword v210, v[4:5], off nt
	global_load_dword v211, v[6:7], off nt
	s_add_i32 s18, s18, 0x8000
	v_add_u32_e32 v28, s18, v2
	v_add_u32_e32 v8, 0xfe000000, v28
	v_lshl_add_u64 v[4:5], v[8:9], 2, v[0:1]
	v_add_u32_e32 v8, 0xfe001000, v28
	v_lshl_add_u64 v[6:7], v[8:9], 2, v[0:1]
	v_add_u32_e32 v8, 0xfe002000, v28
	global_load_dword v212, v[4:5], off nt
	global_load_dword v213, v[6:7], off nt
	v_lshl_add_u64 v[4:5], v[8:9], 2, v[0:1]
	v_add_u32_e32 v8, 0xfe003000, v28
	v_lshl_add_u64 v[6:7], v[8:9], 2, v[0:1]
	v_add_u32_e32 v8, 0xfe004000, v28
	global_load_dword v214, v[4:5], off nt
	global_load_dword v215, v[6:7], off nt
	v_lshl_add_u64 v[4:5], v[8:9], 2, v[0:1]
	v_add_u32_e32 v8, 0xfe005000, v28
	v_lshl_add_u64 v[6:7], v[8:9], 2, v[0:1]
	v_add_u32_e32 v8, 0xfe006000, v28
	global_load_dword v216, v[4:5], off nt
	global_load_dword v217, v[6:7], off nt
	v_lshl_add_u64 v[4:5], v[8:9], 2, v[0:1]
	v_add_u32_e32 v8, 0xfe007000, v28
	v_lshl_add_u64 v[6:7], v[8:9], 2, v[0:1]
	global_load_dword v218, v[4:5], off nt
	global_load_dword v219, v[6:7], off nt
	s_add_i32 s18, s18, 0x8000
	v_mov_b32_e32 v220, v3
	v_add_u32_e32 v221, 0x400, v220
	s_waitcnt vmcnt(30)
	ds_write2_b32 v220, v188, v189 offset1:66
	s_waitcnt vmcnt(28)
	ds_write2_b32 v220, v190, v191 offset0:132 offset1:198
	s_waitcnt vmcnt(26)
	ds_write2_b32 v221, v192, v193 offset0:8 offset1:74
	s_waitcnt vmcnt(24)
	ds_write2_b32 v221, v194, v195 offset0:140 offset1:206
	v_add_u32_e32 v220, 0x840, v220
	v_add_u32_e32 v221, 0x400, v220
	s_waitcnt vmcnt(22)
	ds_write2_b32 v220, v196, v197 offset1:66
	s_waitcnt vmcnt(20)
	ds_write2_b32 v220, v198, v199 offset0:132 offset1:198
	s_waitcnt vmcnt(18)
	ds_write2_b32 v221, v200, v201 offset0:8 offset1:74
	s_waitcnt vmcnt(16)
	ds_write2_b32 v221, v202, v203 offset0:140 offset1:206
	v_add_u32_e32 v220, 0x840, v220
	v_add_u32_e32 v221, 0x400, v220
	s_waitcnt vmcnt(14)
	ds_write2_b32 v220, v204, v205 offset1:66
	s_waitcnt vmcnt(12)
	ds_write2_b32 v220, v206, v207 offset0:132 offset1:198
	s_waitcnt vmcnt(10)
	ds_write2_b32 v221, v208, v209 offset0:8 offset1:74
	s_waitcnt vmcnt(8)
; #define LAS __attribute__((address_space(3)))
; #define LDS_WAIT() asm volatile("s_waitcnt lgkmcnt(0)" ::: "memory")
; __device__ __forceinline__ unsigned pk2(float lo, float hi) { return f2bf(lo) | (f2bf(hi) << 16); }
; template <bool NT_STORE> __device__ __forceinline__ void p0_transpose_item(const float* W, int ldw, int src_col0, bf16* WT, int K, int dst_row0, int k0, LAS float* scr, int lane, const float* kscale = nullptr) {
; #pragma unroll 8
;     for (int i = 0; i < 32; ++i) { const int kk = 2 * i + (lane >> 5); scr[kk * 33 + (lane & 31)] = __builtin_nontemporal_load(W + (size_t)(k0 + kk) * ldw + src_col0 + (lane & 31)); }
;     LDS_WAIT(); asm volatile("" ::: "memory");
;     const int c = lane & 7;
;     f32x4 ga = {1.f, 1.f, 1.f, 1.f}, gb = {1.f, 1.f, 1.f, 1.f};
;     if (kscale) { ga = *(const f32x4*)(kscale + k0 + 8 * c); gb = *(const f32x4*)(kscale + k0 + 8 * c + 4); }
; #pragma unroll
;     for (int j = 0; j < 4; ++j) { const int n = (lane >> 3) + 8 * j; const LAS float* s = scr + (8 * c) * 33 + n;
;         v4u o; o.x = pk2(s[0 * 33] * ga.x, s[1 * 33] * ga.y); o.y = pk2(s[2 * 33] * ga.z, s[3 * 33] * ga.w); o.z = pk2(s[4 * 33] * gb.x, s[5 * 33] * gb.y); o.w = pk2(s[6 * 33] * gb.z, s[7 * 33] * gb.w);
;         if (NT_STORE) __builtin_nontemporal_store(o, (v4u*)(WT + (size_t)(dst_row0 + n) * K + k0 + 8 * c)); else *(v4u*)(WT + (size_t)(dst_row0 + n) * K + k0 + 8 * c) = o; }
;     LDS_WAIT(); asm volatile("" ::: "memory");
	ds_write2_b32 v221, v210, v211 offset0:140 offset1:206
	v_add_u32_e32 v220, 0x840, v220
	v_add_u32_e32 v221, 0x400, v220
	s_waitcnt vmcnt(6)
	ds_write2_b32 v220, v212, v213 offset1:66
	s_waitcnt vmcnt(4)
	ds_write2_b32 v220, v214, v215 offset0:132 offset1:198
	s_waitcnt vmcnt(2)
	ds_write2_b32 v221, v216, v217 offset0:8 offset1:74
	s_waitcnt vmcnt(0)
	ds_write2_b32 v221, v218, v219 offset0:140 offset1:206
	v_add_u32_e32 v220, 0x840, v220
	v_add_u32_e32 v3, 0x2100, v3
	s_waitcnt lgkmcnt(0)
	ds_read2_b32 v[4:5], v38 offset1:8
	ds_read2_b32 v[28:29], v38 offset0:33 offset1:41
	ds_read2_b32 v[30:31], v38 offset0:66 offset1:74
	ds_read2_b32 v[32:33], v38 offset0:99 offset1:107
	ds_read2_b32 v[34:35], v38 offset0:132 offset1:140
	s_waitcnt lgkmcnt(4)
	v_bfe_u32 v0, v4, 16, 1
	v_add3_u32 v0, v4, v0, s1
	s_waitcnt lgkmcnt(3)
	v_bfe_u32 v1, v28, 16, 1
	v_lshrrev_b32_e32 v0, 16, v0
	v_add3_u32 v1, v28, v1, s1
	ds_read2_b32 v[52:53], v38 offset0:165 offset1:173
	v_and_or_b32 v0, v1, s5, v0
	s_waitcnt lgkmcnt(3)
	v_bfe_u32 v1, v30, 16, 1
	v_add3_u32 v1, v30, v1, s1
	s_waitcnt lgkmcnt(2)
	v_bfe_u32 v2, v32, 16, 1
	ds_read2_b32 v[54:55], v38 offset0:198 offset1:206
	v_lshrrev_b32_e32 v1, 16, v1
	v_add3_u32 v2, v32, v2, s1
	ds_read2_b32 v[56:57], v38 offset0:231 offset1:239
	v_and_or_b32 v1, v2, s5, v1
	s_waitcnt lgkmcnt(3)
	v_bfe_u32 v2, v34, 16, 1
	v_add3_u32 v2, v34, v2, s1
	s_waitcnt lgkmcnt(2)
	v_bfe_u32 v3, v52, 16, 1
	v_lshrrev_b32_e32 v2, 16, v2
	v_add3_u32 v3, v52, v3, s1
	v_and_or_b32 v2, v3, s5, v2
	s_waitcnt lgkmcnt(1)
	v_bfe_u32 v3, v54, 16, 1
	v_add3_u32 v3, v54, v3, s1
	s_waitcnt lgkmcnt(0)
	v_bfe_u32 v4, v56, 16, 1
	s_and_b32 s18, s26, 0x7fffffc0
	v_lshrrev_b32_e32 v3, 16, v3
	v_add3_u32 v4, v56, v4, s1
	s_addk_i32 s18, 0xc000
	v_and_or_b32 v3, v4, s5, v3
	v_or_b32_e32 v4, s22, v37
	v_lshl_add_u64 v[6:7], s[18:19], 1, v[12:13]
	v_lshlrev_b32_e32 v8, 14, v4
	v_lshl_add_u64 v[58:59], v[6:7], 0, v[8:9]
	global_store_dwordx4 v[58:59], v[0:3], off nt
	v_bfe_u32 v4, v57, 16, 1
	v_or_b32_e32 v8, s22, v39
	v_bfe_u32 v0, v5, 16, 1
	v_add3_u32 v0, v5, v0, s1
	v_bfe_u32 v1, v29, 16, 1
	v_lshrrev_b32_e32 v0, 16, v0
	v_add3_u32 v1, v29, v1, s1
	v_and_or_b32 v0, v1, s5, v0
	v_bfe_u32 v1, v31, 16, 1
	v_add3_u32 v1, v31, v1, s1
	v_bfe_u32 v2, v33, 16, 1
	v_lshrrev_b32_e32 v1, 16, v1
	v_add3_u32 v2, v33, v2, s1
	v_and_or_b32 v1, v2, s5, v1
	v_bfe_u32 v2, v35, 16, 1
	v_add3_u32 v2, v35, v2, s1
	v_bfe_u32 v3, v53, 16, 1
	v_lshrrev_b32_e32 v2, 16, v2
	v_add3_u32 v3, v53, v3, s1
	v_and_or_b32 v2, v3, s5, v2
	v_bfe_u32 v3, v55, 16, 1
	v_add3_u32 v3, v55, v3, s1
	v_lshrrev_b32_e32 v3, 16, v3
	v_add3_u32 v4, v57, v4, s1
	v_lshlrev_b32_e32 v8, 14, v8
	v_and_or_b32 v3, v4, s5, v3
	ds_read2_b32 v[4:5], v38 offset0:16 offset1:24
	v_lshl_add_u64 v[28:29], v[6:7], 0, v[8:9]
	global_store_dwordx4 v[28:29], v[0:3], off nt
	ds_read2_b32 v[28:29], v38 offset0:49 offset1:57
	ds_read2_b32 v[30:31], v38 offset0:82 offset1:90
	ds_read2_b32 v[32:33], v38 offset0:115 offset1:123
	s_waitcnt lgkmcnt(3)
	v_bfe_u32 v0, v4, 16, 1
	v_add3_u32 v0, v4, v0, s1
	s_waitcnt lgkmcnt(2)
	v_bfe_u32 v1, v28, 16, 1
	ds_read2_b32 v[34:35], v38 offset0:148 offset1:156
	v_lshrrev_b32_e32 v0, 16, v0
	v_add3_u32 v1, v28, v1, s1
	ds_read2_b32 v[52:53], v38 offset0:181 offset1:189
	v_and_or_b32 v0, v1, s5, v0
	s_waitcnt lgkmcnt(3)
	v_bfe_u32 v1, v30, 16, 1
	v_add3_u32 v1, v30, v1, s1
	s_waitcnt lgkmcnt(2)
	v_bfe_u32 v2, v32, 16, 1
	ds_read2_b32 v[54:55], v38 offset0:214 offset1:222
	v_lshrrev_b32_e32 v1, 16, v1
	v_add3_u32 v2, v32, v2, s1
	ds_read2_b32 v[56:57], v38 offset0:247 offset1:255
	v_and_or_b32 v1, v2, s5, v1
	s_waitcnt lgkmcnt(3)
	v_bfe_u32 v2, v34, 16, 1
	v_add3_u32 v2, v34, v2, s1
	s_waitcnt lgkmcnt(2)
	v_bfe_u32 v3, v52, 16, 1
	v_lshrrev_b32_e32 v2, 16, v2
	v_add3_u32 v3, v52, v3, s1
	v_and_or_b32 v2, v3, s5, v2
	s_waitcnt lgkmcnt(1)
	v_bfe_u32 v3, v54, 16, 1
	v_add3_u32 v3, v54, v3, s1
	s_waitcnt lgkmcnt(0)
	v_bfe_u32 v4, v56, 16, 1
	v_lshrrev_b32_e32 v3, 16, v3
	v_add3_u32 v4, v56, v4, s1
	v_and_or_b32 v3, v4, s5, v3
	v_or_b32_e32 v4, s22, v40
	v_lshlrev_b32_e32 v8, 14, v4
	v_lshl_add_u64 v[58:59], v[6:7], 0, v[8:9]
	global_store_dwordx4 v[58:59], v[0:3], off nt
	v_bfe_u32 v4, v57, 16, 1
	v_add3_u32 v4, v57, v4, s1
	v_bfe_u32 v0, v5, 16, 1
	v_add3_u32 v0, v5, v0, s1
	v_bfe_u32 v1, v29, 16, 1
	v_lshrrev_b32_e32 v0, 16, v0
	v_add3_u32 v1, v29, v1, s1
	v_and_or_b32 v0, v1, s5, v0
	v_bfe_u32 v1, v31, 16, 1
	v_add3_u32 v1, v31, v1, s1
	v_bfe_u32 v2, v33, 16, 1
	v_lshrrev_b32_e32 v1, 16, v1
	v_add3_u32 v2, v33, v2, s1
	v_and_or_b32 v1, v2, s5, v1
	v_bfe_u32 v2, v35, 16, 1
	v_add3_u32 v2, v35, v2, s1
	v_bfe_u32 v3, v53, 16, 1
	v_lshrrev_b32_e32 v2, 16, v2
	v_add3_u32 v3, v53, v3, s1
	v_and_or_b32 v2, v3, s5, v2
	v_bfe_u32 v3, v55, 16, 1
	v_add3_u32 v3, v55, v3, s1
	v_lshrrev_b32_e32 v3, 16, v3
	v_and_or_b32 v3, v4, s5, v3
	v_or_b32_e32 v4, s22, v41
	v_lshlrev_b32_e32 v8, 14, v4
	v_lshl_add_u64 v[4:5], v[6:7], 0, v[8:9]
	global_store_dwordx4 v[4:5], v[0:3], off nt
	s_waitcnt lgkmcnt(0)
	s_mov_b64 s[22:23], 0

; #define LDS_WAIT() asm volatile("s_waitcnt lgkmcnt(0)" ::: "memory")
; template <bool NT_STORE> __device__ __forceinline__ void p0_transpose_item(const float* W, int ldw, int src_col0, bf16* WT, int K, int dst_row0, int k0, LAS float* scr, int lane, const float* kscale = nullptr) {
; #pragma unroll 8
;     for (int i = 0; i < 32; ++i) { const int kk = 2 * i + (lane >> 5); scr[kk * 33 + (lane & 31)] = __builtin_nontemporal_load(W + (size_t)(k0 + kk) * ldw + src_col0 + (lane & 31)); }
;     LDS_WAIT(); asm volatile("" ::: "memory");
;     const int c = lane & 7;
;     f32x4 ga = {1.f, 1.f, 1.f, 1.f}, gb = {1.f, 1.f, 1.f, 1.f};
;     if (kscale) { ga = *(const f32x4*)(kscale + k0 + 8 * c); gb = *(const f32x4*)(kscale + k0 + 8 * c + 4); }
.LBB0_40:
	v_add_u32_e32 v8, s18, v2
	v_mov_b32_e32 v5, v9
	v_mov_b32_e32 v7, v9
	v_mov_b32_e32 v29, v9
	v_mov_b32_e32 v31, v9
	v_add_u32_e32 v4, 0x4000, v8
	v_add_u32_e32 v6, 0x8000, v8
	v_add_u32_e32 v28, 0xc000, v8
	v_add_u32_e32 v30, 0x10000, v8
	v_mov_b32_e32 v33, v9
	v_mov_b32_e32 v35, v9
	v_lshl_add_u64 v[52:53], v[8:9], 2, v[0:1]
	v_add_u32_e32 v32, 0x14000, v8
	v_add_u32_e32 v34, 0x18000, v8
	v_add_u32_e32 v8, 0x1c000, v8
	v_lshl_add_u64 v[4:5], v[4:5], 2, v[0:1]
	v_lshl_add_u64 v[6:7], v[6:7], 2, v[0:1]
	v_lshl_add_u64 v[28:29], v[28:29], 2, v[0:1]
	v_lshl_add_u64 v[30:31], v[30:31], 2, v[0:1]
	v_lshl_add_u64 v[32:33], v[32:33], 2, v[0:1]
	v_lshl_add_u64 v[34:35], v[34:35], 2, v[0:1]
	v_lshl_add_u64 v[54:55], v[8:9], 2, v[0:1]
	global_load_dword v188, v[52:53], off nt
	global_load_dword v189, v[4:5], off nt
	global_load_dword v190, v[6:7], off nt
	global_load_dword v191, v[28:29], off nt
	global_load_dword v192, v[30:31], off nt
	global_load_dword v193, v[32:33], off nt
	global_load_dword v194, v[34:35], off nt
	global_load_dword v195, v[54:55], off nt
	s_add_i32 s18, s18, 0x20000
	v_add_u32_e32 v8, s18, v2
	v_mov_b32_e32 v5, v9
	v_mov_b32_e32 v7, v9
	v_mov_b32_e32 v29, v9
	v_mov_b32_e32 v31, v9
	v_add_u32_e32 v4, 0x4000, v8
	v_add_u32_e32 v6, 0x8000, v8
	v_add_u32_e32 v28, 0xc000, v8
	v_add_u32_e32 v30, 0x10000, v8
	v_mov_b32_e32 v33, v9
	v_mov_b32_e32 v35, v9
	v_lshl_add_u64 v[52:53], v[8:9], 2, v[0:1]
	v_add_u32_e32 v32, 0x14000, v8
	v_add_u32_e32 v34, 0x18000, v8
	v_add_u32_e32 v8, 0x1c000, v8
	v_lshl_add_u64 v[4:5], v[4:5], 2, v[0:1]
	v_lshl_add_u64 v[6:7], v[6:7], 2, v[0:1]
	v_lshl_add_u64 v[28:29], v[28:29], 2, v[0:1]
	v_lshl_add_u64 v[30:31], v[30:31], 2, v[0:1]
	v_lshl_add_u64 v[32:33], v[32:33], 2, v[0:1]
	v_lshl_add_u64 v[34:35], v[34:35], 2, v[0:1]
	v_lshl_add_u64 v[54:55], v[8:9], 2, v[0:1]
	global_load_dword v196, v[52:53], off nt
	global_load_dword v197, v[4:5], off nt
	global_load_dword v198, v[6:7], off nt
	global_load_dword v199, v[28:29], off nt
	global_load_dword v200, v[30:31], off nt
	global_load_dword v201, v[32:33], off nt
	global_load_dword v202, v[34:35], off nt
	global_load_dword v203, v[54:55], off nt
	s_add_i32 s18, s18, 0x20000
	v_add_u32_e32 v8, s18, v2
	v_mov_b32_e32 v5, v9
	v_mov_b32_e32 v7, v9
	v_mov_b32_e32 v29, v9
	v_mov_b32_e32 v31, v9
	v_add_u32_e32 v4, 0x4000, v8
	v_add_u32_e32 v6, 0x8000, v8
	v_add_u32_e32 v28, 0xc000, v8
	v_add_u32_e32 v30, 0x10000, v8
	v_mov_b32_e32 v33, v9
	v_mov_b32_e32 v35, v9
	v_lshl_add_u64 v[52:53], v[8:9], 2, v[0:1]
	v_add_u32_e32 v32, 0x14000, v8
	v_add_u32_e32 v34, 0x18000, v8
	v_add_u32_e32 v8, 0x1c000, v8
	v_lshl_add_u64 v[4:5], v[4:5], 2, v[0:1]
	v_lshl_add_u64 v[6:7], v[6:7], 2, v[0:1]
	v_lshl_add_u64 v[28:29], v[28:29], 2, v[0:1]
	v_lshl_add_u64 v[30:31], v[30:31], 2, v[0:1]
	v_lshl_add_u64 v[32:33], v[32:33], 2, v[0:1]
	v_lshl_add_u64 v[34:35], v[34:35], 2, v[0:1]
	v_lshl_add_u64 v[54:55], v[8:9], 2, v[0:1]
	global_load_dword v204, v[52:53], off nt
	global_load_dword v205, v[4:5], off nt
	global_load_dword v206, v[6:7], off nt
	global_load_dword v207, v[28:29], off nt
	global_load_dword v208, v[30:31], off nt
	global_load_dword v209, v[32:33], off nt
	global_load_dword v210, v[34:35], off nt
	global_load_dword v211, v[54:55], off nt
	s_add_i32 s18, s18, 0x20000
	v_add_u32_e32 v8, s18, v2
	v_mov_b32_e32 v5, v9
	v_mov_b32_e32 v7, v9
	v_mov_b32_e32 v29, v9
	v_mov_b32_e32 v31, v9
	v_add_u32_e32 v4, 0x4000, v8
	v_add_u32_e32 v6, 0x8000, v8
	v_add_u32_e32 v28, 0xc000, v8
	v_add_u32_e32 v30, 0x10000, v8
	v_mov_b32_e32 v33, v9
	v_mov_b32_e32 v35, v9
	v_lshl_add_u64 v[52:53], v[8:9], 2, v[0:1]
	v_add_u32_e32 v32, 0x14000, v8
	v_add_u32_e32 v34, 0x18000, v8
	v_add_u32_e32 v8, 0x1c000, v8
	v_lshl_add_u64 v[4:5], v[4:5], 2, v[0:1]
	v_lshl_add_u64 v[6:7], v[6:7], 2, v[0:1]
	v_lshl_add_u64 v[28:29], v[28:29], 2, v[0:1]
	v_lshl_add_u64 v[30:31], v[30:31], 2, v[0:1]
	v_lshl_add_u64 v[32:33], v[32:33], 2, v[0:1]
	v_lshl_add_u64 v[34:35], v[34:35], 2, v[0:1]
	v_lshl_add_u64 v[54:55], v[8:9], 2, v[0:1]
	global_load_dword v212, v[52:53], off nt
	global_load_dword v213, v[4:5], off nt
	global_load_dword v214, v[6:7], off nt
	global_load_dword v215, v[28:29], off nt
	global_load_dword v216, v[30:31], off nt
	global_load_dword v217, v[32:33], off nt
	global_load_dword v218, v[34:35], off nt
	global_load_dword v219, v[54:55], off nt
	s_add_i32 s18, s18, 0x20000
	v_mov_b32_e32 v220, v3
	v_add_u32_e32 v221, 0x400, v220
	s_waitcnt vmcnt(30)
	ds_write2_b32 v220, v188, v189 offset1:66
	s_waitcnt vmcnt(28)
	ds_write2_b32 v220, v190, v191 offset0:132 offset1:198
	s_waitcnt vmcnt(26)
	ds_write2_b32 v221, v192, v193 offset0:8 offset1:74
	s_waitcnt vmcnt(24)
	ds_write2_b32 v221, v194, v195 offset0:140 offset1:206
	v_add_u32_e32 v220, 0x840, v220
	v_add_u32_e32 v221, 0x400, v220
	s_waitcnt vmcnt(22)
	ds_write2_b32 v220, v196, v197 offset1:66
	s_waitcnt vmcnt(20)
	ds_write2_b32 v220, v198, v199 offset0:132 offset1:198
	s_waitcnt vmcnt(18)
	ds_write2_b32 v221, v200, v201 offset0:8 offset1:74
	s_waitcnt vmcnt(16)
	ds_write2_b32 v221, v202, v203 offset0:140 offset1:206
	v_add_u32_e32 v220, 0x840, v220
	v_add_u32_e32 v221, 0x400, v220
	s_waitcnt vmcnt(14)
	ds_write2_b32 v220, v204, v205 offset1:66
	s_waitcnt vmcnt(12)
	ds_write2_b32 v220, v206, v207 offset0:132 offset1:198
	s_waitcnt vmcnt(10)
	ds_write2_b32 v221, v208, v209 offset0:8 offset1:74
	s_waitcnt vmcnt(8)
	ds_write2_b32 v221, v210, v211 offset0:140 offset1:206
	v_add_u32_e32 v220, 0x840, v220
	v_add_u32_e32 v221, 0x400, v220
	s_waitcnt vmcnt(6)
	ds_write2_b32 v220, v212, v213 offset1:66
	s_waitcnt vmcnt(4)
	ds_write2_b32 v220, v214, v215 offset0:132 offset1:198
	s_waitcnt vmcnt(2)
	ds_write2_b32 v221, v216, v217 offset0:8 offset1:74
	s_waitcnt vmcnt(0)
	ds_write2_b32 v221, v218, v219 offset0:140 offset1:206
	v_add_u32_e32 v220, 0x840, v220
	v_add_u32_e32 v3, 0x2100, v3
	s_waitcnt lgkmcnt(0)
	s_add_i32 s18, s26, 0xffffe000
	s_lshr_b32 s18, s18, 2
	s_and_b32 s23, s18, 0x3fffffc0
	s_and_b64 vcc, exec, s[20:21]
	s_cbranch_vccz .LBB0_43
	s_lshl_b32 s18, s23, 2
	v_lshl_add_u64 v[4:5], v[16:17], 0, s[18:19]
	global_load_dwordx4 v[0:3], v[4:5], off offset:16
	s_nop 0
	global_load_dwordx4 v[4:7], v[4:5], off
	s_waitcnt vmcnt(1)
	v_mov_b32_e32 v28, v1
	v_mov_b32_e32 v1, v2
	v_mov_b32_e32 v29, v3
	s_waitcnt vmcnt(0)
	v_mov_b32_e32 v2, v5
	v_mov_b32_e32 v5, v6
	v_mov_b32_e32 v3, v7
	s_branch .LBB0_44

; #define LAS __attribute__((address_space(3)))
; #define LDS_WAIT() asm volatile("s_waitcnt lgkmcnt(0)" ::: "memory")
; template <bool NT_STORE> __device__ __forceinline__ void p0_transpose_item(const float* W, int ldw, int src_col0, bf16* WT, int K, int dst_row0, int k0, LAS float* scr, int lane, const float* kscale = nullptr) {
; #pragma unroll 8
;     for (int i = 0; i < 32; ++i) { const int kk = 2 * i + (lane >> 5); scr[kk * 33 + (lane & 31)] = __builtin_nontemporal_load(W + (size_t)(k0 + kk) * ldw + src_col0 + (lane & 31)); }
;     LDS_WAIT(); asm volatile("" ::: "memory");
.LBB0_48:
	v_add_u32_e32 v28, s18, v2
	v_add_u32_e32 v8, 0xff400000, v28
	v_lshl_add_u64 v[4:5], v[8:9], 2, v[0:1]
	v_add_u32_e32 v8, 0xff401000, v28
	v_lshl_add_u64 v[6:7], v[8:9], 2, v[0:1]
	v_add_u32_e32 v8, 0xff402000, v28
	global_load_dword v188, v[4:5], off nt
	global_load_dword v189, v[6:7], off nt
	v_lshl_add_u64 v[4:5], v[8:9], 2, v[0:1]
	v_add_u32_e32 v8, 0xff403000, v28
	v_lshl_add_u64 v[6:7], v[8:9], 2, v[0:1]
	v_add_u32_e32 v8, 0xff404000, v28
	global_load_dword v190, v[4:5], off nt
	global_load_dword v191, v[6:7], off nt
	v_lshl_add_u64 v[4:5], v[8:9], 2, v[0:1]
	v_add_u32_e32 v8, 0xff405000, v28
	v_lshl_add_u64 v[6:7], v[8:9], 2, v[0:1]
	v_add_u32_e32 v8, 0xff406000, v28
	global_load_dword v192, v[4:5], off nt
	global_load_dword v193, v[6:7], off nt
	v_lshl_add_u64 v[4:5], v[8:9], 2, v[0:1]
	v_add_u32_e32 v8, 0xff407000, v28
	v_lshl_add_u64 v[6:7], v[8:9], 2, v[0:1]
	global_load_dword v194, v[4:5], off nt
	global_load_dword v195, v[6:7], off nt
	s_add_i32 s18, s18, 0x8000
	v_add_u32_e32 v28, s18, v2
	v_add_u32_e32 v8, 0xff400000, v28
	v_lshl_add_u64 v[4:5], v[8:9], 2, v[0:1]
	v_add_u32_e32 v8, 0xff401000, v28
	v_lshl_add_u64 v[6:7], v[8:9], 2, v[0:1]
	v_add_u32_e32 v8, 0xff402000, v28
	global_load_dword v196, v[4:5], off nt
	global_load_dword v197, v[6:7], off nt
	v_lshl_add_u64 v[4:5], v[8:9], 2, v[0:1]
	v_add_u32_e32 v8, 0xff403000, v28
	v_lshl_add_u64 v[6:7], v[8:9], 2, v[0:1]
	v_add_u32_e32 v8, 0xff404000, v28
	global_load_dword v198, v[4:5], off nt
	global_load_dword v199, v[6:7], off nt
	v_lshl_add_u64 v[4:5], v[8:9], 2, v[0:1]
	v_add_u32_e32 v8, 0xff405000, v28
	v_lshl_add_u64 v[6:7], v[8:9], 2, v[0:1]
	v_add_u32_e32 v8, 0xff406000, v28
	global_load_dword v200, v[4:5], off nt
	global_load_dword v201, v[6:7], off nt
	v_lshl_add_u64 v[4:5], v[8:9], 2, v[0:1]
	v_add_u32_e32 v8, 0xff407000, v28
	v_lshl_add_u64 v[6:7], v[8:9], 2, v[0:1]
	global_load_dword v202, v[4:5], off nt
	global_load_dword v203, v[6:7], off nt
	s_add_i32 s18, s18, 0x8000
	v_add_u32_e32 v28, s18, v2
	v_add_u32_e32 v8, 0xff400000, v28
	v_lshl_add_u64 v[4:5], v[8:9], 2, v[0:1]
	v_add_u32_e32 v8, 0xff401000, v28
	v_lshl_add_u64 v[6:7], v[8:9], 2, v[0:1]
	v_add_u32_e32 v8, 0xff402000, v28
	global_load_dword v204, v[4:5], off nt
	global_load_dword v205, v[6:7], off nt
	v_lshl_add_u64 v[4:5], v[8:9], 2, v[0:1]
	v_add_u32_e32 v8, 0xff403000, v28
	v_lshl_add_u64 v[6:7], v[8:9], 2, v[0:1]
	v_add_u32_e32 v8, 0xff404000, v28
	global_load_dword v206, v[4:5], off nt
	global_load_dword v207, v[6:7], off nt
	v_lshl_add_u64 v[4:5], v[8:9], 2, v[0:1]
	v_add_u32_e32 v8, 0xff405000, v28
	v_lshl_add_u64 v[6:7], v[8:9], 2, v[0:1]
	v_add_u32_e32 v8, 0xff406000, v28
	global_load_dword v208, v[4:5], off nt
	global_load_dword v209, v[6:7], off nt
	v_lshl_add_u64 v[4:5], v[8:9], 2, v[0:1]
	v_add_u32_e32 v8, 0xff407000, v28
	v_lshl_add_u64 v[6:7], v[8:9], 2, v[0:1]
	global_load_dword v210, v[4:5], off nt
	global_load_dword v211, v[6:7], off nt
	s_add_i32 s18, s18, 0x8000
	v_add_u32_e32 v28, s18, v2
	v_add_u32_e32 v8, 0xff400000, v28
	v_lshl_add_u64 v[4:5], v[8:9], 2, v[0:1]
	v_add_u32_e32 v8, 0xff401000, v28
	v_lshl_add_u64 v[6:7], v[8:9], 2, v[0:1]
	v_add_u32_e32 v8, 0xff402000, v28
	global_load_dword v212, v[4:5], off nt
	global_load_dword v213, v[6:7], off nt
	v_lshl_add_u64 v[4:5], v[8:9], 2, v[0:1]
	v_add_u32_e32 v8, 0xff403000, v28
	v_lshl_add_u64 v[6:7], v[8:9], 2, v[0:1]
	v_add_u32_e32 v8, 0xff404000, v28
	global_load_dword v214, v[4:5], off nt
	global_load_dword v215, v[6:7], off nt
	v_lshl_add_u64 v[4:5], v[8:9], 2, v[0:1]
	v_add_u32_e32 v8, 0xff405000, v28
	v_lshl_add_u64 v[6:7], v[8:9], 2, v[0:1]
	v_add_u32_e32 v8, 0xff406000, v28
	global_load_dword v216, v[4:5], off nt
	global_load_dword v217, v[6:7], off nt
	v_lshl_add_u64 v[4:5], v[8:9], 2, v[0:1]
	v_add_u32_e32 v8, 0xff407000, v28
	v_lshl_add_u64 v[6:7], v[8:9], 2, v[0:1]
	global_load_dword v218, v[4:5], off nt
	global_load_dword v219, v[6:7], off nt
	s_add_i32 s18, s18, 0x8000
	v_mov_b32_e32 v220, v3
	v_add_u32_e32 v221, 0x400, v220
	s_waitcnt vmcnt(30)
	ds_write2_b32 v220, v188, v189 offset1:66
	s_waitcnt vmcnt(28)
	ds_write2_b32 v220, v190, v191 offset0:132 offset1:198
	s_waitcnt vmcnt(26)
	ds_write2_b32 v221, v192, v193 offset0:8 offset1:74
	s_waitcnt vmcnt(24)
	ds_write2_b32 v221, v194, v195 offset0:140 offset1:206
	v_add_u32_e32 v220, 0x840, v220
	v_add_u32_e32 v221, 0x400, v220
	s_waitcnt vmcnt(22)
	ds_write2_b32 v220, v196, v197 offset1:66
	s_waitcnt vmcnt(20)
	ds_write2_b32 v220, v198, v199 offset0:132 offset1:198
	s_waitcnt vmcnt(18)
	ds_write2_b32 v221, v200, v201 offset0:8 offset1:74
	s_waitcnt vmcnt(16)
	ds_write2_b32 v221, v202, v203 offset0:140 offset1:206
	v_add_u32_e32 v220, 0x840, v220
	v_add_u32_e32 v221, 0x400, v220
	s_waitcnt vmcnt(14)
	ds_write2_b32 v220, v204, v205 offset1:66
	s_waitcnt vmcnt(12)
	ds_write2_b32 v220, v206, v207 offset0:132 offset1:198
	s_waitcnt vmcnt(10)
	ds_write2_b32 v221, v208, v209 offset0:8 offset1:74
	s_waitcnt vmcnt(8)
; #define LAS __attribute__((address_space(3)))
; #define LDS_WAIT() asm volatile("s_waitcnt lgkmcnt(0)" ::: "memory")
; __device__ __forceinline__ unsigned pk2(float lo, float hi) { return f2bf(lo) | (f2bf(hi) << 16); }
; template <bool NT_STORE> __device__ __forceinline__ void p0_transpose_item(const float* W, int ldw, int src_col0, bf16* WT, int K, int dst_row0, int k0, LAS float* scr, int lane, const float* kscale = nullptr) {
; #pragma unroll 8
;     for (int i = 0; i < 32; ++i) { const int kk = 2 * i + (lane >> 5); scr[kk * 33 + (lane & 31)] = __builtin_nontemporal_load(W + (size_t)(k0 + kk) * ldw + src_col0 + (lane & 31)); }
;     LDS_WAIT(); asm volatile("" ::: "memory");
;     const int c = lane & 7;
;     f32x4 ga = {1.f, 1.f, 1.f, 1.f}, gb = {1.f, 1.f, 1.f, 1.f};
;     if (kscale) { ga = *(const f32x4*)(kscale + k0 + 8 * c); gb = *(const f32x4*)(kscale + k0 + 8 * c + 4); }
; #pragma unroll
;     for (int j = 0; j < 4; ++j) { const int n = (lane >> 3) + 8 * j; const LAS float* s = scr + (8 * c) * 33 + n;
;         v4u o; o.x = pk2(s[0 * 33] * ga.x, s[1 * 33] * ga.y); o.y = pk2(s[2 * 33] * ga.z, s[3 * 33] * ga.w); o.z = pk2(s[4 * 33] * gb.x, s[5 * 33] * gb.y); o.w = pk2(s[6 * 33] * gb.z, s[7 * 33] * gb.w);
;         if (NT_STORE) __builtin_nontemporal_store(o, (v4u*)(WT + (size_t)(dst_row0 + n) * K + k0 + 8 * c)); else *(v4u*)(WT + (size_t)(dst_row0 + n) * K + k0 + 8 * c) = o; }
;     LDS_WAIT(); asm volatile("" ::: "memory");
	ds_write2_b32 v221, v210, v211 offset0:140 offset1:206
	v_add_u32_e32 v220, 0x840, v220
	v_add_u32_e32 v221, 0x400, v220
	s_waitcnt vmcnt(6)
	ds_write2_b32 v220, v212, v213 offset1:66
	s_waitcnt vmcnt(4)
	ds_write2_b32 v220, v214, v215 offset0:132 offset1:198
	s_waitcnt vmcnt(2)
	ds_write2_b32 v221, v216, v217 offset0:8 offset1:74
	s_waitcnt vmcnt(0)
	ds_write2_b32 v221, v218, v219 offset0:140 offset1:206
	v_add_u32_e32 v220, 0x840, v220
	v_add_u32_e32 v3, 0x2100, v3
	s_waitcnt lgkmcnt(0)
	ds_read2_b32 v[4:5], v38 offset1:8
	ds_read2_b32 v[28:29], v38 offset0:33 offset1:41
	ds_read2_b32 v[30:31], v38 offset0:66 offset1:74
	ds_read2_b32 v[32:33], v38 offset0:99 offset1:107
	ds_read2_b32 v[34:35], v38 offset0:132 offset1:140
	s_waitcnt lgkmcnt(4)
	v_bfe_u32 v0, v4, 16, 1
	v_add3_u32 v0, v4, v0, s1
	s_waitcnt lgkmcnt(3)
	v_bfe_u32 v1, v28, 16, 1
	v_lshrrev_b32_e32 v0, 16, v0
	v_add3_u32 v1, v28, v1, s1
	ds_read2_b32 v[52:53], v38 offset0:165 offset1:173
	v_and_or_b32 v0, v1, s5, v0
	s_waitcnt lgkmcnt(3)
	v_bfe_u32 v1, v30, 16, 1
	v_add3_u32 v1, v30, v1, s1
	s_waitcnt lgkmcnt(2)
	v_bfe_u32 v2, v32, 16, 1
	ds_read2_b32 v[54:55], v38 offset0:198 offset1:206
	v_lshrrev_b32_e32 v1, 16, v1
	v_add3_u32 v2, v32, v2, s1
	ds_read2_b32 v[56:57], v38 offset0:231 offset1:239
	v_and_or_b32 v1, v2, s5, v1
	s_waitcnt lgkmcnt(3)
	v_bfe_u32 v2, v34, 16, 1
	v_add3_u32 v2, v34, v2, s1
	s_waitcnt lgkmcnt(2)
	v_bfe_u32 v3, v52, 16, 1
	v_lshrrev_b32_e32 v2, 16, v2
	v_add3_u32 v3, v52, v3, s1
	v_and_or_b32 v2, v3, s5, v2
	s_waitcnt lgkmcnt(1)
	v_bfe_u32 v3, v54, 16, 1
	v_add3_u32 v3, v54, v3, s1
	s_waitcnt lgkmcnt(0)
	v_bfe_u32 v4, v56, 16, 1
	s_and_b32 s18, s26, 0x1fc0
	v_lshrrev_b32_e32 v3, 16, v3
	v_add3_u32 v4, v56, v4, s1
	s_addk_i32 s18, 0xe800
	v_and_or_b32 v3, v4, s5, v3
	v_or_b32_e32 v4, s22, v37
	v_lshl_add_u64 v[6:7], s[18:19], 1, v[20:21]
	v_lshlrev_b32_e32 v8, 12, v4
	v_lshl_add_u64 v[58:59], v[6:7], 0, v[8:9]
	global_store_dwordx4 v[58:59], v[0:3], off nt
	v_bfe_u32 v4, v57, 16, 1
	v_or_b32_e32 v8, s22, v39
	v_bfe_u32 v0, v5, 16, 1
	v_add3_u32 v0, v5, v0, s1
	v_bfe_u32 v1, v29, 16, 1
	v_lshrrev_b32_e32 v0, 16, v0
	v_add3_u32 v1, v29, v1, s1
	v_and_or_b32 v0, v1, s5, v0
	v_bfe_u32 v1, v31, 16, 1
	v_add3_u32 v1, v31, v1, s1
	v_bfe_u32 v2, v33, 16, 1
	v_lshrrev_b32_e32 v1, 16, v1
	v_add3_u32 v2, v33, v2, s1
	v_and_or_b32 v1, v2, s5, v1
	v_bfe_u32 v2, v35, 16, 1
	v_add3_u32 v2, v35, v2, s1
	v_bfe_u32 v3, v53, 16, 1
	v_lshrrev_b32_e32 v2, 16, v2
	v_add3_u32 v3, v53, v3, s1
	v_and_or_b32 v2, v3, s5, v2
	v_bfe_u32 v3, v55, 16, 1
	v_add3_u32 v3, v55, v3, s1
	v_lshrrev_b32_e32 v3, 16, v3
	v_add3_u32 v4, v57, v4, s1
	v_lshlrev_b32_e32 v8, 12, v8
	v_and_or_b32 v3, v4, s5, v3
	ds_read2_b32 v[4:5], v38 offset0:16 offset1:24
	v_lshl_add_u64 v[28:29], v[6:7], 0, v[8:9]
	global_store_dwordx4 v[28:29], v[0:3], off nt
	ds_read2_b32 v[28:29], v38 offset0:49 offset1:57
	ds_read2_b32 v[30:31], v38 offset0:82 offset1:90
	ds_read2_b32 v[32:33], v38 offset0:115 offset1:123
	s_waitcnt lgkmcnt(3)
	v_bfe_u32 v0, v4, 16, 1
	v_add3_u32 v0, v4, v0, s1
	s_waitcnt lgkmcnt(2)
	v_bfe_u32 v1, v28, 16, 1
	ds_read2_b32 v[34:35], v38 offset0:148 offset1:156
	v_lshrrev_b32_e32 v0, 16, v0
	v_add3_u32 v1, v28, v1, s1
	ds_read2_b32 v[52:53], v38 offset0:181 offset1:189
	v_and_or_b32 v0, v1, s5, v0
	s_waitcnt lgkmcnt(3)
	v_bfe_u32 v1, v30, 16, 1
	v_add3_u32 v1, v30, v1, s1
	s_waitcnt lgkmcnt(2)
	v_bfe_u32 v2, v32, 16, 1
	ds_read2_b32 v[54:55], v38 offset0:214 offset1:222
	v_lshrrev_b32_e32 v1, 16, v1
	v_add3_u32 v2, v32, v2, s1
	ds_read2_b32 v[56:57], v38 offset0:247 offset1:255
	v_and_or_b32 v1, v2, s5, v1
	s_waitcnt lgkmcnt(3)
	v_bfe_u32 v2, v34, 16, 1
	v_add3_u32 v2, v34, v2, s1
	s_waitcnt lgkmcnt(2)
	v_bfe_u32 v3, v52, 16, 1
	v_lshrrev_b32_e32 v2, 16, v2
	v_add3_u32 v3, v52, v3, s1
	v_and_or_b32 v2, v3, s5, v2
	s_waitcnt lgkmcnt(1)
	v_bfe_u32 v3, v54, 16, 1
	v_add3_u32 v3, v54, v3, s1
	s_waitcnt lgkmcnt(0)
	v_bfe_u32 v4, v56, 16, 1
	v_lshrrev_b32_e32 v3, 16, v3
	v_add3_u32 v4, v56, v4, s1
	v_and_or_b32 v3, v4, s5, v3
	v_or_b32_e32 v4, s22, v40
	v_lshlrev_b32_e32 v8, 12, v4
	v_lshl_add_u64 v[58:59], v[6:7], 0, v[8:9]
	global_store_dwordx4 v[58:59], v[0:3], off nt
	v_bfe_u32 v4, v57, 16, 1
	v_add3_u32 v4, v57, v4, s1
	v_bfe_u32 v0, v5, 16, 1
	v_add3_u32 v0, v5, v0, s1
	v_bfe_u32 v1, v29, 16, 1
	v_lshrrev_b32_e32 v0, 16, v0
	v_add3_u32 v1, v29, v1, s1
	v_and_or_b32 v0, v1, s5, v0
	v_bfe_u32 v1, v31, 16, 1
	v_add3_u32 v1, v31, v1, s1
	v_bfe_u32 v2, v33, 16, 1
	v_lshrrev_b32_e32 v1, 16, v1
	v_add3_u32 v2, v33, v2, s1
	v_and_or_b32 v1, v2, s5, v1
	v_bfe_u32 v2, v35, 16, 1
	v_add3_u32 v2, v35, v2, s1
	v_bfe_u32 v3, v53, 16, 1
	v_lshrrev_b32_e32 v2, 16, v2
	v_add3_u32 v3, v53, v3, s1
	v_and_or_b32 v2, v3, s5, v2
	v_bfe_u32 v3, v55, 16, 1
	v_add3_u32 v3, v55, v3, s1
	v_lshrrev_b32_e32 v3, 16, v3
	v_and_or_b32 v3, v4, s5, v3
	v_or_b32_e32 v4, s22, v41
	v_lshlrev_b32_e32 v8, 12, v4
	v_lshl_add_u64 v[4:5], v[6:7], 0, v[8:9]
	global_store_dwordx4 v[4:5], v[0:3], off nt
	s_waitcnt lgkmcnt(0)

; #define LAS __attribute__((address_space(3)))
; #define LDS_WAIT() asm volatile("s_waitcnt lgkmcnt(0)" ::: "memory")
; template <bool NT_STORE> __device__ __forceinline__ void p0_transpose_item(const float* W, int ldw, int src_col0, bf16* WT, int K, int dst_row0, int k0, LAS float* scr, int lane, const float* kscale = nullptr) {
; #pragma unroll 8
;     for (int i = 0; i < 32; ++i) { const int kk = 2 * i + (lane >> 5); scr[kk * 33 + (lane & 31)] = __builtin_nontemporal_load(W + (size_t)(k0 + kk) * ldw + src_col0 + (lane & 31)); }
;     LDS_WAIT(); asm volatile("" ::: "memory");
.LBB0_64:
	v_lshl_add_u64 v[52:53], v[34:35], 0, s[22:23]
	v_lshl_add_u64 v[54:55], v[32:33], 0, s[22:23]
	v_lshl_add_u64 v[56:57], v[30:31], 0, s[22:23]
	v_lshl_add_u64 v[58:59], v[28:29], 0, s[22:23]
	v_lshl_add_u64 v[60:61], v[6:7], 0, s[22:23]
	v_lshl_add_u64 v[62:63], v[4:5], 0, s[22:23]
	v_lshl_add_u64 v[64:65], v[2:3], 0, s[22:23]
	v_lshl_add_u64 v[66:67], v[0:1], 0, s[22:23]
	global_load_dword v188, v[52:53], off nt
	global_load_dword v189, v[54:55], off nt
	global_load_dword v190, v[56:57], off nt
	global_load_dword v191, v[58:59], off nt
	global_load_dword v192, v[60:61], off nt
	global_load_dword v193, v[62:63], off nt
	global_load_dword v194, v[64:65], off nt
	global_load_dword v195, v[66:67], off nt
	s_add_u32 s22, s22, 0x60000
	s_addc_u32 s23, s23, 0
	v_lshl_add_u64 v[52:53], v[34:35], 0, s[22:23]
	v_lshl_add_u64 v[54:55], v[32:33], 0, s[22:23]
	v_lshl_add_u64 v[56:57], v[30:31], 0, s[22:23]
	v_lshl_add_u64 v[58:59], v[28:29], 0, s[22:23]
	v_lshl_add_u64 v[60:61], v[6:7], 0, s[22:23]
	v_lshl_add_u64 v[62:63], v[4:5], 0, s[22:23]
	v_lshl_add_u64 v[64:65], v[2:3], 0, s[22:23]
	v_lshl_add_u64 v[66:67], v[0:1], 0, s[22:23]
	global_load_dword v196, v[52:53], off nt
	global_load_dword v197, v[54:55], off nt
	global_load_dword v198, v[56:57], off nt
	global_load_dword v199, v[58:59], off nt
	global_load_dword v200, v[60:61], off nt
	global_load_dword v201, v[62:63], off nt
	global_load_dword v202, v[64:65], off nt
	global_load_dword v203, v[66:67], off nt
	s_add_u32 s22, s22, 0x60000
	s_addc_u32 s23, s23, 0
	v_lshl_add_u64 v[52:53], v[34:35], 0, s[22:23]
	v_lshl_add_u64 v[54:55], v[32:33], 0, s[22:23]
	v_lshl_add_u64 v[56:57], v[30:31], 0, s[22:23]
	v_lshl_add_u64 v[58:59], v[28:29], 0, s[22:23]
	v_lshl_add_u64 v[60:61], v[6:7], 0, s[22:23]
	v_lshl_add_u64 v[62:63], v[4:5], 0, s[22:23]
	v_lshl_add_u64 v[64:65], v[2:3], 0, s[22:23]
	v_lshl_add_u64 v[66:67], v[0:1], 0, s[22:23]
	global_load_dword v204, v[52:53], off nt
	global_load_dword v205, v[54:55], off nt
	global_load_dword v206, v[56:57], off nt
	global_load_dword v207, v[58:59], off nt
	global_load_dword v208, v[60:61], off nt
	global_load_dword v209, v[62:63], off nt
	global_load_dword v210, v[64:65], off nt
	global_load_dword v211, v[66:67], off nt
	s_add_u32 s22, s22, 0x60000
	s_addc_u32 s23, s23, 0
	v_lshl_add_u64 v[52:53], v[34:35], 0, s[22:23]
	v_lshl_add_u64 v[54:55], v[32:33], 0, s[22:23]
	v_lshl_add_u64 v[56:57], v[30:31], 0, s[22:23]
	v_lshl_add_u64 v[58:59], v[28:29], 0, s[22:23]
	v_lshl_add_u64 v[60:61], v[6:7], 0, s[22:23]
	v_lshl_add_u64 v[62:63], v[4:5], 0, s[22:23]
	v_lshl_add_u64 v[64:65], v[2:3], 0, s[22:23]
	v_lshl_add_u64 v[66:67], v[0:1], 0, s[22:23]
	global_load_dword v212, v[52:53], off nt
	global_load_dword v213, v[54:55], off nt
	global_load_dword v214, v[56:57], off nt
	global_load_dword v215, v[58:59], off nt
	global_load_dword v216, v[60:61], off nt
	global_load_dword v217, v[62:63], off nt
	global_load_dword v218, v[64:65], off nt
	global_load_dword v219, v[66:67], off nt
	s_add_u32 s22, s22, 0x60000
	s_addc_u32 s23, s23, 0
	v_mov_b32_e32 v220, v8
	v_add_u32_e32 v221, 0x400, v220
	s_waitcnt vmcnt(30)
	ds_write2_b32 v220, v188, v189 offset1:66
	s_waitcnt vmcnt(28)
	ds_write2_b32 v220, v190, v191 offset0:132 offset1:198
	s_waitcnt vmcnt(26)
	ds_write2_b32 v221, v192, v193 offset0:8 offset1:74
	s_waitcnt vmcnt(24)
	ds_write2_b32 v221, v194, v195 offset0:140 offset1:206
	v_add_u32_e32 v220, 0x840, v220
	v_add_u32_e32 v221, 0x400, v220
	s_waitcnt vmcnt(22)
	ds_write2_b32 v220, v196, v197 offset1:66
	s_waitcnt vmcnt(20)
	ds_write2_b32 v220, v198, v199 offset0:132 offset1:198
	s_waitcnt vmcnt(18)
	ds_write2_b32 v221, v200, v201 offset0:8 offset1:74
	s_waitcnt vmcnt(16)
	ds_write2_b32 v221, v202, v203 offset0:140 offset1:206
	v_add_u32_e32 v220, 0x840, v220
	v_add_u32_e32 v221, 0x400, v220
	s_waitcnt vmcnt(14)
	ds_write2_b32 v220, v204, v205 offset1:66
	s_waitcnt vmcnt(12)
	ds_write2_b32 v220, v206, v207 offset0:132 offset1:198
	s_waitcnt vmcnt(10)
	ds_write2_b32 v221, v208, v209 offset0:8 offset1:74
	s_waitcnt vmcnt(8)
	ds_write2_b32 v221, v210, v211 offset0:140 offset1:206
	v_add_u32_e32 v220, 0x840, v220
	v_add_u32_e32 v221, 0x400, v220
	s_waitcnt vmcnt(6)
	ds_write2_b32 v220, v212, v213 offset1:66
	s_waitcnt vmcnt(4)
	ds_write2_b32 v220, v214, v215 offset0:132 offset1:198
	s_waitcnt vmcnt(2)
	ds_write2_b32 v221, v216, v217 offset0:8 offset1:74
	s_waitcnt vmcnt(0)
	ds_write2_b32 v221, v218, v219 offset0:140 offset1:206
	v_add_u32_e32 v220, 0x840, v220
	v_add_u32_e32 v8, 0x2100, v8
	s_waitcnt lgkmcnt(0)
; #define LAS __attribute__((address_space(3)))
; #define LDS_WAIT() asm volatile("s_waitcnt lgkmcnt(0)" ::: "memory")
; __device__ __forceinline__ unsigned pk2(float lo, float hi) { return f2bf(lo) | (f2bf(hi) << 16); }
; template <bool NT_STORE> __device__ __forceinline__ void p0_transpose_item(const float* W, int ldw, int src_col0, bf16* WT, int K, int dst_row0, int k0, LAS float* scr, int lane, const float* kscale = nullptr) {
;     ...
;     for (int j = 0; j < 4; ++j) { const int n = (lane >> 3) + 8 * j; const LAS float* s = scr + (8 * c) * 33 + n;
;         v4u o; o.x = pk2(s[0 * 33] * ga.x, s[1 * 33] * ga.y); o.y = pk2(s[2 * 33] * ga.z, s[3 * 33] * ga.w); o.z = pk2(s[4 * 33] * gb.x, s[5 * 33] * gb.y); o.w = pk2(s[6 * 33] * gb.z, s[7 * 33] * gb.w);
;         if (NT_STORE) __builtin_nontemporal_store(o, (v4u*)(WT + (size_t)(dst_row0 + n) * K + k0 + 8 * c)); else *(v4u*)(WT + (size_t)(dst_row0 + n) * K + k0 + 8 * c) = o; }
;     LDS_WAIT(); asm volatile("" ::: "memory");
; }
; __global__ void __launch_bounds__(NWAVES * 64, 2) fwd(Params P) {
;     ...
;         for (int it = gw; it < NITEMS; it += NGW) {
;             int r = it;
;             if (r < I_IN) { const int kb = r / 192, nb = r % 192; p0_transpose_item<false>(w_in, 6144, 32 * nb, POOL, 2048, win_dst_row(32 * nb), 64 * kb, scr, lane); continue; } r -= I_IN;
	ds_read2_b32 v[4:5], v38 offset1:8
	ds_read2_b32 v[28:29], v38 offset0:33 offset1:41
	ds_read2_b32 v[30:31], v38 offset0:66 offset1:74
	ds_read2_b32 v[32:33], v38 offset0:99 offset1:107
	ds_read2_b32 v[34:35], v38 offset0:132 offset1:140
	ds_read2_b32 v[52:53], v38 offset0:165 offset1:173
	s_waitcnt lgkmcnt(5)
	v_bfe_u32 v0, v4, 16, 1
	v_add3_u32 v0, v4, v0, s1
	s_waitcnt lgkmcnt(4)
	v_bfe_u32 v1, v28, 16, 1
	v_lshrrev_b32_e32 v0, 16, v0
	v_add3_u32 v1, v28, v1, s1
	v_and_or_b32 v0, v1, s5, v0
	s_waitcnt lgkmcnt(3)
	v_bfe_u32 v1, v30, 16, 1
	v_add3_u32 v1, v30, v1, s1
	s_waitcnt lgkmcnt(2)
	v_bfe_u32 v2, v32, 16, 1
	ds_read2_b32 v[54:55], v38 offset0:198 offset1:206
	v_lshrrev_b32_e32 v1, 16, v1
	v_add3_u32 v2, v32, v2, s1
	ds_read2_b32 v[56:57], v38 offset0:231 offset1:239
	v_and_or_b32 v1, v2, s5, v1
	s_waitcnt lgkmcnt(3)
	v_bfe_u32 v2, v34, 16, 1
	v_add3_u32 v2, v34, v2, s1
	s_waitcnt lgkmcnt(2)
	v_bfe_u32 v3, v52, 16, 1
	v_lshrrev_b32_e32 v2, 16, v2
	v_add3_u32 v3, v52, v3, s1
	v_and_or_b32 v2, v3, s5, v2
	s_waitcnt lgkmcnt(1)
	v_bfe_u32 v3, v54, 16, 1
	v_add_u32_e32 v58, s18, v37
	s_ashr_i32 s25, s24, 31
	v_add3_u32 v3, v54, v3, s1
	s_waitcnt lgkmcnt(0)
	v_bfe_u32 v4, v56, 16, 1
	v_ashrrev_i32_e32 v59, 31, v58
	v_lshl_add_u64 v[6:7], s[24:25], 1, v[22:23]
	v_lshrrev_b32_e32 v3, 16, v3
	v_add3_u32 v4, v56, v4, s1
	v_lshlrev_b64 v[58:59], 12, v[58:59]
	v_and_or_b32 v3, v4, s5, v3
	v_lshl_add_u64 v[58:59], v[6:7], 0, v[58:59]
	global_store_dwordx4 v[58:59], v[0:3], off
	v_bfe_u32 v4, v57, 16, 1
	v_add3_u32 v4, v57, v4, s1
	v_bfe_u32 v0, v5, 16, 1
	v_add3_u32 v0, v5, v0, s1
	v_bfe_u32 v1, v29, 16, 1
	v_lshrrev_b32_e32 v0, 16, v0
	v_add3_u32 v1, v29, v1, s1
	v_and_or_b32 v0, v1, s5, v0
	v_bfe_u32 v1, v31, 16, 1
	v_add3_u32 v1, v31, v1, s1
	v_bfe_u32 v2, v33, 16, 1
	v_lshrrev_b32_e32 v1, 16, v1
	v_add3_u32 v2, v33, v2, s1
	v_and_or_b32 v1, v2, s5, v1
	v_bfe_u32 v2, v35, 16, 1
	v_add3_u32 v2, v35, v2, s1
	v_bfe_u32 v3, v53, 16, 1
	v_lshrrev_b32_e32 v2, 16, v2
	v_add3_u32 v3, v53, v3, s1
	v_and_or_b32 v2, v3, s5, v2
	v_bfe_u32 v3, v55, 16, 1
	v_add3_u32 v3, v55, v3, s1
	v_lshrrev_b32_e32 v3, 16, v3
	v_and_or_b32 v3, v4, s5, v3
	v_add_u32_e32 v4, s18, v39
	v_ashrrev_i32_e32 v5, 31, v4
	v_lshlrev_b64 v[4:5], 12, v[4:5]
	ds_read2_b32 v[28:29], v38 offset0:16 offset1:24
	v_lshl_add_u64 v[4:5], v[6:7], 0, v[4:5]
	global_store_dwordx4 v[4:5], v[0:3], off
	ds_read2_b32 v[4:5], v38 offset0:49 offset1:57
	ds_read2_b32 v[30:31], v38 offset0:82 offset1:90
	ds_read2_b32 v[32:33], v38 offset0:115 offset1:123
	s_waitcnt lgkmcnt(3)
	v_bfe_u32 v0, v28, 16, 1
	v_add3_u32 v0, v28, v0, s1
	s_waitcnt lgkmcnt(2)
	v_bfe_u32 v1, v4, 16, 1
	ds_read2_b32 v[34:35], v38 offset0:148 offset1:156
	v_lshrrev_b32_e32 v0, 16, v0
	v_add3_u32 v1, v4, v1, s1
	ds_read2_b32 v[52:53], v38 offset0:181 offset1:189
	v_and_or_b32 v0, v1, s5, v0
	s_waitcnt lgkmcnt(3)
	v_bfe_u32 v1, v30, 16, 1
	v_add3_u32 v1, v30, v1, s1
	s_waitcnt lgkmcnt(2)
	v_bfe_u32 v2, v32, 16, 1
	ds_read2_b32 v[54:55], v38 offset0:214 offset1:222
	v_lshrrev_b32_e32 v1, 16, v1
	v_add3_u32 v2, v32, v2, s1
	ds_read2_b32 v[56:57], v38 offset0:247 offset1:255
	v_and_or_b32 v1, v2, s5, v1
	s_waitcnt lgkmcnt(3)
	v_bfe_u32 v2, v34, 16, 1
	v_add3_u32 v2, v34, v2, s1
	s_waitcnt lgkmcnt(2)
	v_bfe_u32 v3, v52, 16, 1
	v_lshrrev_b32_e32 v2, 16, v2
	v_add3_u32 v3, v52, v3, s1
	v_and_or_b32 v2, v3, s5, v2
	s_waitcnt lgkmcnt(1)
	v_bfe_u32 v3, v54, 16, 1
	v_add_u32_e32 v58, s18, v40
	v_add3_u32 v3, v54, v3, s1
	s_waitcnt lgkmcnt(0)
	v_bfe_u32 v4, v56, 16, 1
	v_ashrrev_i32_e32 v59, 31, v58
	v_lshrrev_b32_e32 v3, 16, v3
	v_add3_u32 v4, v56, v4, s1
	v_lshlrev_b64 v[58:59], 12, v[58:59]
	v_and_or_b32 v3, v4, s5, v3
	v_lshl_add_u64 v[58:59], v[6:7], 0, v[58:59]
	global_store_dwordx4 v[58:59], v[0:3], off
	v_bfe_u32 v4, v57, 16, 1
	v_add3_u32 v4, v57, v4, s1
	v_bfe_u32 v0, v29, 16, 1
	v_add3_u32 v0, v29, v0, s1
	v_bfe_u32 v1, v5, 16, 1
	v_lshrrev_b32_e32 v0, 16, v0
	v_add3_u32 v1, v5, v1, s1
	v_and_or_b32 v0, v1, s5, v0
	v_bfe_u32 v1, v31, 16, 1
	v_add3_u32 v1, v31, v1, s1
	v_bfe_u32 v2, v33, 16, 1
	v_lshrrev_b32_e32 v1, 16, v1
	v_add3_u32 v2, v33, v2, s1
	v_and_or_b32 v1, v2, s5, v1
	v_bfe_u32 v2, v35, 16, 1
	v_add3_u32 v2, v35, v2, s1
	v_bfe_u32 v3, v53, 16, 1
	v_lshrrev_b32_e32 v2, 16, v2
	v_add3_u32 v3, v53, v3, s1
	v_and_or_b32 v2, v3, s5, v2
	v_bfe_u32 v3, v55, 16, 1
	v_add3_u32 v3, v55, v3, s1
	v_lshrrev_b32_e32 v3, 16, v3
	v_and_or_b32 v3, v4, s5, v3
	v_add_u32_e32 v4, s18, v41
	v_ashrrev_i32_e32 v5, 31, v4
	v_lshlrev_b64 v[4:5], 12, v[4:5]
	v_lshl_add_u64 v[4:5], v[6:7], 0, v[4:5]
	global_store_dwordx4 v[4:5], v[0:3], off
	s_waitcnt lgkmcnt(0)
	s_branch .LBB0_30
